# PEER follower lookahead threshold raised to 5 units
# speedup vs baseline: 1.1610x; 1.0041x over previous
.Lxp_chka:
	s_bitcmp1_b32 s2, 31
	s_cbranch_scc1 .Lxp_goa
	s_sub_i32 s3, s83, s2
	s_and_b32 s3, s3, 0x3fff
	s_cmp_lt_u32 s3, 0x2000
	s_cbranch_scc0 .Lxp_goa
	s_cmp_gt_u32 s3, 0x280
	s_cbranch_scc0 .Lxp_goa
	s_sub_i32 vcc_lo, vcc_lo, 1
	s_cmp_eq_u32 vcc_lo, 0
	s_cbranch_scc1 .Lxp_goa
	s_sleep 8
	global_load_dword v132, v[246:247], off sc1
	s_waitcnt vmcnt(0)
	v_readfirstlane_b32 s2, v132
	s_branch .Lxp_chka
